# v83 + N2 q-loop: dropped three leftover vmcnt(0) between the four YSC stores (pure store-ack drains after the row-load hoist)
# baseline (speedup 1.0000x reference)
; __device__ __forceinline__ unsigned pk2(float lo, float hi) { return pg8::cvt_pk_bf16(lo, hi); }
; __device__ __forceinline__ float blo(unsigned w) { return __uint_as_float(w << 16); }
; __device__ __forceinline__ float bhi(unsigned w) { return __uint_as_float(w & 0xffff0000u); }
; __device__ __forceinline__ void n2_phase(unsigned char* ws, int layer, int gw, int NGW, int lane) {
;     ...
; #pragma unroll
;             for (int rr = 0; rr < 4; ++rr) {
;                 const v4u cv = *(const v4u*)(proj + (size_t)(r0 + rr) * NP + PC_SCC + c);
;                 float a[8];
; #pragma unroll
;                 for (int j = 0; j < 8; ++j) a[j] = wk[0][j] * pr[rr][j] + wk[1][j] * pr[rr + 1][j] + wk[2][j] * pr[rr + 2][j];
;                 v4u o; o.x = pk2(blo(cv.x) * a[0], bhi(cv.x) * a[1]); o.y = pk2(blo(cv.y) * a[2], bhi(cv.y) * a[3]); o.z = pk2(blo(cv.z) * a[4], bhi(cv.z) * a[5]); o.w = pk2(blo(cv.w) * a[6], bhi(cv.w) * a[7]);
;                 *(v4u*)(ysc + (size_t)(r0 + rr) * D + c) = o;
;             }
.LBB0_756:
	v_add_co_u32_e32 v104, vcc, s3, v104
	s_waitcnt vmcnt(3)
	v_pk_mul_f32 v[114:115], v[18:19], v[72:73]
	v_addc_co_u32_e32 v105, vcc, 0, v105, vcc
	v_mov_b32_e32 v110, v168
	v_mov_b32_e32 v111, v169
	v_mov_b32_e32 v112, v170
	v_mov_b32_e32 v113, v171
	v_pk_mul_f32 v[104:105], v[16:17], v[78:79]
	v_pk_fma_f32 v[86:87], v[14:15], v[86:87], v[114:115]
	v_pk_fma_f32 v[84:85], v[12:13], v[84:85], v[104:105]
	s_waitcnt vmcnt(2)
	v_pk_fma_f32 v[86:87], v[22:23], v[62:63], v[86:87]
	v_pk_fma_f32 v[84:85], v[20:21], v[66:67], v[84:85]
	v_pk_mul_f32 v[116:117], v[4:5], v[68:69]
	v_pk_mul_f32 v[118:119], v[6:7], v[56:57]
	s_mov_b64 s[24:25], 0x800
	v_lshl_add_u64 v[48:49], v[48:49], 0, s[24:25]
	v_lshl_add_u64 v[36:37], v[36:37], 0, s[62:63]
	v_lshl_add_u64 v[38:39], v[38:39], 0, s[62:63]
	v_lshl_add_u64 v[40:41], v[40:41], 0, s[62:63]
	v_lshl_add_u64 v[42:43], v[42:43], 0, s[62:63]
	v_lshl_add_u64 v[44:45], v[44:45], 0, s[62:63]
	v_lshl_add_u64 v[46:47], v[46:47], 0, s[62:63]
	s_waitcnt vmcnt(0)
	v_lshlrev_b32_e32 v104, 16, v110
	v_and_b32_e32 v105, 0xffff0000, v110
	v_pk_mul_f32 v[84:85], v[84:85], v[104:105]
	v_lshlrev_b32_e32 v104, 16, v111
	v_and_b32_e32 v105, 0xffff0000, v111
	v_pk_mul_f32 v[86:87], v[86:87], v[104:105]
	v_cvt_pk_bf16_f32 v84, v84, v85
	v_cvt_pk_bf16_f32 v85, v86, v87
	v_pk_fma_f32 v[86:87], v[0:1], v[88:89], v[116:117]
	v_lshlrev_b32_e32 v88, 16, v112
	v_pk_fma_f32 v[86:87], v[8:9], v[60:61], v[86:87]
	v_and_b32_e32 v89, 0xffff0000, v112
	v_pk_mul_f32 v[86:87], v[86:87], v[88:89]
	v_pk_fma_f32 v[88:89], v[2:3], v[90:91], v[118:119]
	v_lshlrev_b32_e32 v90, 16, v113
	v_pk_fma_f32 v[88:89], v[10:11], v[64:65], v[88:89]
	v_and_b32_e32 v91, 0xffff0000, v113
	v_pk_mul_f32 v[88:89], v[88:89], v[90:91]
	v_cvt_pk_bf16_f32 v86, v86, v87
	v_cvt_pk_bf16_f32 v87, v88, v89
	v_lshl_add_u64 v[88:89], v[34:35], 0, s[0:1]
	global_store_dwordx4 v[88:89], v[84:87], off
	v_pk_mul_f32 v[88:89], v[16:17], v[66:67]
	s_add_u32 s0, s0, 0x400
	v_add_co_u32_e32 v84, vcc, s3, v102
	v_pk_fma_f32 v[78:79], v[12:13], v[78:79], v[88:89]
	s_nop 0
	v_addc_co_u32_e32 v85, vcc, 0, v103, vcc
	v_mov_b32_e32 v84, v172
	v_mov_b32_e32 v85, v173
	v_mov_b32_e32 v86, v174
	v_mov_b32_e32 v87, v175
	v_pk_fma_f32 v[78:79], v[20:21], v[58:59], v[78:79]
	s_addc_u32 s1, s1, 0
	v_lshlrev_b32_e32 v88, 16, v84
	v_and_b32_e32 v89, 0xffff0000, v84
	v_pk_mul_f32 v[78:79], v[78:79], v[88:89]
	s_nop 0
	v_cvt_pk_bf16_f32 v84, v78, v79
	v_pk_mul_f32 v[78:79], v[18:19], v[62:63]
	s_nop 0
	v_pk_fma_f32 v[72:73], v[14:15], v[72:73], v[78:79]
	v_lshlrev_b32_e32 v78, 16, v85
	v_pk_fma_f32 v[72:73], v[22:23], v[54:55], v[72:73]
	v_and_b32_e32 v79, 0xffff0000, v85
	v_pk_mul_f32 v[72:73], v[72:73], v[78:79]
	s_nop 0
	v_cvt_pk_bf16_f32 v85, v72, v73
	v_pk_mul_f32 v[72:73], v[4:5], v[60:61]
	s_nop 0
	v_pk_fma_f32 v[68:69], v[0:1], v[68:69], v[72:73]
	v_lshlrev_b32_e32 v72, 16, v86
	v_pk_fma_f32 v[68:69], v[8:9], v[52:53], v[68:69]
	v_and_b32_e32 v73, 0xffff0000, v86
	v_pk_mul_f32 v[68:69], v[68:69], v[72:73]
	s_nop 0
	v_cvt_pk_bf16_f32 v86, v68, v69
	v_pk_mul_f32 v[68:69], v[6:7], v[64:65]
	s_nop 0
	v_pk_fma_f32 v[56:57], v[2:3], v[56:57], v[68:69]
	v_lshlrev_b32_e32 v68, 16, v87
	v_pk_fma_f32 v[56:57], v[10:11], v[50:51], v[56:57]
	v_and_b32_e32 v69, 0xffff0000, v87
	v_pk_mul_f32 v[56:57], v[56:57], v[68:69]
	s_nop 0
	v_cvt_pk_bf16_f32 v87, v56, v57
	v_lshl_add_u64 v[56:57], v[34:35], 0, s[16:17]
	global_store_dwordx4 v[56:57], v[84:87], off
	v_add_co_u32_e32 v56, vcc, s3, v100
	s_add_u32 s16, s16, 0x400
	s_nop 0
	v_addc_co_u32_e32 v57, vcc, 0, v101, vcc
	v_mov_b32_e32 v84, v176
	v_mov_b32_e32 v85, v177
	v_mov_b32_e32 v86, v178
	v_mov_b32_e32 v87, v179
	v_pk_mul_f32 v[56:57], v[16:17], v[58:59]
	v_pk_mul_f32 v[16:17], v[16:17], v[82:83]
	v_pk_fma_f32 v[56:57], v[12:13], v[66:67], v[56:57]
	v_pk_fma_f32 v[12:13], v[12:13], v[58:59], v[16:17]
	v_pk_fma_f32 v[56:57], v[20:21], v[82:83], v[56:57]
	v_pk_fma_f32 v[12:13], v[20:21], v[98:99], v[12:13]
	s_addc_u32 s17, s17, 0
	v_lshlrev_b32_e32 v66, 16, v84
	v_and_b32_e32 v67, 0xffff0000, v84
	v_pk_mul_f32 v[56:57], v[56:57], v[66:67]
	s_nop 0
	v_cvt_pk_bf16_f32 v66, v56, v57
	v_pk_mul_f32 v[56:57], v[18:19], v[54:55]
	s_nop 0
	v_pk_fma_f32 v[56:57], v[14:15], v[62:63], v[56:57]
	v_lshlrev_b32_e32 v62, 16, v85
	v_pk_fma_f32 v[56:57], v[22:23], v[74:75], v[56:57]
	v_and_b32_e32 v63, 0xffff0000, v85
	v_pk_mul_f32 v[56:57], v[56:57], v[62:63]
	s_nop 0
	v_cvt_pk_bf16_f32 v67, v56, v57
	v_pk_mul_f32 v[56:57], v[4:5], v[52:53]
	v_pk_mul_f32 v[4:5], v[4:5], v[70:71]
	v_pk_fma_f32 v[56:57], v[0:1], v[60:61], v[56:57]
	v_lshlrev_b32_e32 v60, 16, v86
	v_pk_fma_f32 v[56:57], v[8:9], v[70:71], v[56:57]
	v_and_b32_e32 v61, 0xffff0000, v86
	v_pk_mul_f32 v[56:57], v[56:57], v[60:61]
	v_lshlrev_b32_e32 v60, 16, v87
	v_cvt_pk_bf16_f32 v68, v56, v57
	v_pk_mul_f32 v[56:57], v[6:7], v[50:51]
	v_and_b32_e32 v61, 0xffff0000, v87
	v_pk_fma_f32 v[56:57], v[2:3], v[64:65], v[56:57]
	v_pk_fma_f32 v[0:1], v[0:1], v[52:53], v[4:5]
	v_pk_fma_f32 v[56:57], v[10:11], v[76:77], v[56:57]
	v_pk_fma_f32 v[0:1], v[8:9], v[92:93], v[0:1]
	v_pk_mul_f32 v[56:57], v[56:57], v[60:61]
	s_nop 0
	v_cvt_pk_bf16_f32 v69, v56, v57
	v_lshl_add_u64 v[56:57], v[34:35], 0, s[22:23]
	global_store_dwordx4 v[56:57], v[66:69], off
	v_add_co_u32_e32 v56, vcc, s3, v94
	s_add_u32 s22, s22, 0x400
	s_nop 0
	v_addc_co_u32_e32 v57, vcc, 0, v95, vcc
	v_mov_b32_e32 v60, v180
	v_mov_b32_e32 v61, v181
	v_mov_b32_e32 v62, v182
	v_mov_b32_e32 v63, v183
	s_addc_u32 s23, s23, 0
	v_lshlrev_b32_e32 v16, 16, v60
	v_and_b32_e32 v17, 0xffff0000, v60
	v_pk_mul_f32 v[12:13], v[12:13], v[16:17]
	v_pk_mul_f32 v[16:17], v[18:19], v[74:75]
	v_lshlrev_b32_e32 v4, 16, v62
	v_pk_fma_f32 v[14:15], v[14:15], v[54:55], v[16:17]
	v_lshlrev_b32_e32 v16, 16, v61
	v_pk_fma_f32 v[14:15], v[22:23], v[96:97], v[14:15]
	v_and_b32_e32 v17, 0xffff0000, v61
	v_and_b32_e32 v5, 0xffff0000, v62
	v_pk_mul_f32 v[14:15], v[14:15], v[16:17]
	v_pk_mul_f32 v[0:1], v[0:1], v[4:5]
	v_cvt_pk_bf16_f32 v12, v12, v13
	v_cvt_pk_bf16_f32 v13, v14, v15
	v_cvt_pk_bf16_f32 v14, v0, v1
	v_pk_mul_f32 v[0:1], v[6:7], v[76:77]
	s_nop 0
	v_pk_fma_f32 v[0:1], v[2:3], v[50:51], v[0:1]
	v_lshlrev_b32_e32 v2, 16, v63
	v_pk_fma_f32 v[0:1], v[10:11], v[80:81], v[0:1]
	v_and_b32_e32 v3, 0xffff0000, v63
	v_pk_mul_f32 v[0:1], v[0:1], v[2:3]
	s_nop 0
	v_cvt_pk_bf16_f32 v15, v0, v1
	v_lshl_add_u64 v[0:1], v[34:35], 0, s[26:27]
	s_add_u32 s26, s26, 0x400
	s_addc_u32 s27, s27, 0
	s_add_i32 s9, s9, -1
	s_cmp_eq_u32 s9, 0
	global_store_dwordx4 v[0:1], v[12:15], off
	s_cbranch_scc1 .LBB0_752
